# FF1 epilogue stores widened to dwordx4 with v_permlane16_swap pairs (lane and lane+16 exchange their column quads)
# speedup vs baseline: 1.0101x; 1.0060x over previous
.LBB0_90:
	v_mov_b32_e32 v136, s88
	ds_read_b32 v136, v136
	v_readlane_b32 s2, v254, 44
	v_mov_b32_e32 v151, v153
	s_mov_b64 s[58:59], -1
	s_mov_b64 s[56:57], 0
	s_waitcnt lgkmcnt(0)
	v_readfirstlane_b32 s48, v136
	v_mov_b32_e32 v136, s89
	ds_read_b32 v136, v136
	s_add_u32 s52, s48, 0x2100000
	s_waitcnt lgkmcnt(0)
	v_readfirstlane_b32 s49, v136
	v_mov_b32_e32 v136, s2
	ds_read_b32 v136, v136
	v_readlane_b32 s2, v254, 45
	s_addc_u32 s53, s49, 0
	s_add_u32 s46, s48, 0x158d0000
	s_addc_u32 s47, s49, 0
	s_waitcnt lgkmcnt(0)
	v_readfirstlane_b32 s42, v136
	v_mov_b32_e32 v136, s2
	ds_read_b32 v136, v136
	v_readlane_b32 s2, v254, 31
	s_add_u32 s40, s48, 0xc600000
	s_addc_u32 s41, s49, 0
	s_add_u32 s36, s48, 0xe700000
	s_waitcnt lgkmcnt(0)
	v_readfirstlane_b32 s43, v136
	v_mov_b32_e32 v136, s2
	ds_read_b32 v136, v136
	v_readlane_b32 s2, v254, 46
	s_addc_u32 s37, s49, 0
	s_add_u32 s34, s48, 0x6300000
	s_addc_u32 s35, s49, 0
	s_waitcnt lgkmcnt(0)
	v_readfirstlane_b32 s65, v136
	v_mov_b32_e32 v136, s2
	ds_read_b32 v136, v136
	v_readlane_b32 s2, v254, 39
	s_add_u32 s38, s48, 0x4200000
	s_addc_u32 s39, s49, 0
	s_add_u32 s50, s48, 0x15af4000
	s_waitcnt lgkmcnt(0)
	v_readfirstlane_b32 s66, v136
	v_mov_b32_e32 v136, s2
	ds_read_b32 v136, v136
	v_readlane_b32 s2, v254, 48
	s_addc_u32 s51, s49, 0
	s_lshl_b32 s62, s10, 8
	s_lshl_b32 s27, s67, 8
	s_waitcnt lgkmcnt(0)
	v_readfirstlane_b32 s44, v136
	v_mov_b32_e32 v136, s2
	v_readlane_b32 s2, v254, 40
	s_add_i32 s62, s62, s2
	s_ashr_i32 s2, s62, 13
	ds_read_b32 v136, v136
	s_mul_i32 s54, s2, 0x1800
	v_readlane_b32 s2, v254, 26
	s_ashr_i32 s55, s54, 31
	s_mul_i32 s2, s2, 0x12000
	s_add_u32 s2, s48, s2
	v_or_b32_e32 v138, s62, v157
	s_addc_u32 s3, s49, 0
	v_ashrrev_i32_e32 v139, 31, v138
	s_add_u32 s30, s2, 0x15ad0000
	s_waitcnt lgkmcnt(0)
	v_readfirstlane_b32 s45, v136
	v_lshlrev_b64 v[136:137], 13, v[138:139]
	v_add_u32_e32 v150, 0xffffc000, v138
	s_addc_u32 s31, s3, 0
	v_lshl_add_u64 v[148:149], s[52:53], 0, v[136:137]
	v_cmp_gt_i32_e64 s[10:11], s92, v138
	v_cmp_lt_i32_e64 s[8:9], s80, v138
	v_lshlrev_b64 v[146:147], 10, v[150:151]
	v_lshlrev_b64 v[142:143], 10, v[138:139]
	v_or_b32_e32 v136, s27, v161
	s_cmp_lg_u32 s79, 26
	s_cbranch_scc1 .Lff1_no
	v_ashrrev_i32_e32 v137, 31, v136
	v_lshl_add_u64 v[244:245], v[136:137], 1, v[148:149]
	v_mbcnt_lo_u32_b32 v246, -1, 0
	v_mbcnt_hi_u32_b32 v246, -1, v246
	v_and_b32_e32 v246, 16, v246
	v_lshrrev_b32_e32 v247, 1, v246
	v_add_u32_e32 v246, v246, v247
	v_mov_b32_e32 v247, 0
	v_lshl_add_u64 v[244:245], v[246:247], 0, v[244:245]
	v_max_f32_e32 v124, v124, v124
	v_max_f32_e32 v124, 0, v124
	v_mul_f32_e32 v124, v124, v124
	v_max_f32_e32 v125, v125, v125
	v_max_f32_e32 v125, 0, v125
	v_mul_f32_e32 v125, v125, v125
	v_max_f32_e32 v126, v126, v126
	v_max_f32_e32 v126, 0, v126
	v_mul_f32_e32 v126, v126, v126
	v_max_f32_e32 v127, v127, v127
	v_max_f32_e32 v127, 0, v127
	v_mul_f32_e32 v127, v127, v127
	v_max_f32_e32 v120, v120, v120
	v_max_f32_e32 v120, 0, v120
	v_mul_f32_e32 v120, v120, v120
	v_max_f32_e32 v121, v121, v121
	v_max_f32_e32 v121, 0, v121
	v_mul_f32_e32 v121, v121, v121
	v_max_f32_e32 v122, v122, v122
	v_max_f32_e32 v122, 0, v122
	v_mul_f32_e32 v122, v122, v122
	v_max_f32_e32 v123, v123, v123
	v_max_f32_e32 v123, 0, v123
	v_mul_f32_e32 v123, v123, v123
	v_cvt_pk_bf16_f32 v230, v124, v125
	v_cvt_pk_bf16_f32 v231, v126, v127
	v_cvt_pk_bf16_f32 v232, v120, v121
	v_cvt_pk_bf16_f32 v233, v122, v123
	s_nop 1
	v_permlane16_swap_b32 v230, v232
	v_permlane16_swap_b32 v231, v233
	global_store_dwordx4 v[244:245], v[230:233], off
	v_max_f32_e32 v116, v116, v116
	v_max_f32_e32 v116, 0, v116
	v_mul_f32_e32 v116, v116, v116
	v_max_f32_e32 v117, v117, v117
	v_max_f32_e32 v117, 0, v117
	v_mul_f32_e32 v117, v117, v117
	v_max_f32_e32 v118, v118, v118
	v_max_f32_e32 v118, 0, v118
	v_mul_f32_e32 v118, v118, v118
	v_max_f32_e32 v119, v119, v119
	v_max_f32_e32 v119, 0, v119
	v_mul_f32_e32 v119, v119, v119
	v_max_f32_e32 v112, v112, v112
	v_max_f32_e32 v112, 0, v112
	v_mul_f32_e32 v112, v112, v112
	v_max_f32_e32 v113, v113, v113
	v_max_f32_e32 v113, 0, v113
	v_mul_f32_e32 v113, v113, v113
	v_max_f32_e32 v114, v114, v114
	v_max_f32_e32 v114, 0, v114
	v_mul_f32_e32 v114, v114, v114
	v_max_f32_e32 v115, v115, v115
	v_max_f32_e32 v115, 0, v115
	v_mul_f32_e32 v115, v115, v115
	v_cvt_pk_bf16_f32 v234, v116, v117
	v_cvt_pk_bf16_f32 v235, v118, v119
	v_cvt_pk_bf16_f32 v236, v112, v113
	v_cvt_pk_bf16_f32 v237, v114, v115
	v_add_co_u32_e32 v246, vcc, 0x100, v244
	v_addc_co_u32_e32 v247, vcc, 0, v245, vcc
	v_permlane16_swap_b32 v234, v236
	v_permlane16_swap_b32 v235, v237
	global_store_dwordx4 v[246:247], v[234:237], off
	v_max_f32_e32 v108, v108, v108
	v_max_f32_e32 v108, 0, v108
	v_mul_f32_e32 v108, v108, v108
	v_max_f32_e32 v109, v109, v109
	v_max_f32_e32 v109, 0, v109
	v_mul_f32_e32 v109, v109, v109
	v_max_f32_e32 v110, v110, v110
	v_max_f32_e32 v110, 0, v110
	v_mul_f32_e32 v110, v110, v110
	v_max_f32_e32 v111, v111, v111
	v_max_f32_e32 v111, 0, v111
	v_mul_f32_e32 v111, v111, v111
	v_max_f32_e32 v104, v104, v104
	v_max_f32_e32 v104, 0, v104
	v_mul_f32_e32 v104, v104, v104
	v_max_f32_e32 v105, v105, v105
	v_max_f32_e32 v105, 0, v105
	v_mul_f32_e32 v105, v105, v105
	v_max_f32_e32 v106, v106, v106
	v_max_f32_e32 v106, 0, v106
	v_mul_f32_e32 v106, v106, v106
	v_max_f32_e32 v107, v107, v107
	v_max_f32_e32 v107, 0, v107
	v_mul_f32_e32 v107, v107, v107
	v_cvt_pk_bf16_f32 v230, v108, v109
	v_cvt_pk_bf16_f32 v231, v110, v111
	v_cvt_pk_bf16_f32 v232, v104, v105
	v_cvt_pk_bf16_f32 v233, v106, v107
	v_add_co_u32_e32 v246, vcc, 0x20000, v244
	v_addc_co_u32_e32 v247, vcc, 0, v245, vcc
	v_permlane16_swap_b32 v230, v232
	v_permlane16_swap_b32 v231, v233
	global_store_dwordx4 v[246:247], v[230:233], off
	v_max_f32_e32 v100, v100, v100
	v_max_f32_e32 v100, 0, v100
	v_mul_f32_e32 v100, v100, v100
	v_max_f32_e32 v101, v101, v101
	v_max_f32_e32 v101, 0, v101
	v_mul_f32_e32 v101, v101, v101
	v_max_f32_e32 v102, v102, v102
	v_max_f32_e32 v102, 0, v102
	v_mul_f32_e32 v102, v102, v102
	v_max_f32_e32 v103, v103, v103
	v_max_f32_e32 v103, 0, v103
	v_mul_f32_e32 v103, v103, v103
	v_max_f32_e32 v96, v96, v96
	v_max_f32_e32 v96, 0, v96
	v_mul_f32_e32 v96, v96, v96
	v_max_f32_e32 v97, v97, v97
	v_max_f32_e32 v97, 0, v97
	v_mul_f32_e32 v97, v97, v97
	v_max_f32_e32 v98, v98, v98
	v_max_f32_e32 v98, 0, v98
	v_mul_f32_e32 v98, v98, v98
	v_max_f32_e32 v99, v99, v99
	v_max_f32_e32 v99, 0, v99
	v_mul_f32_e32 v99, v99, v99
	v_cvt_pk_bf16_f32 v234, v100, v101
	v_cvt_pk_bf16_f32 v235, v102, v103
	v_cvt_pk_bf16_f32 v236, v96, v97
	v_cvt_pk_bf16_f32 v237, v98, v99
	v_add_co_u32_e32 v246, vcc, 0x20100, v244
	v_addc_co_u32_e32 v247, vcc, 0, v245, vcc
	v_permlane16_swap_b32 v234, v236
	v_permlane16_swap_b32 v235, v237
	global_store_dwordx4 v[246:247], v[234:237], off
	v_max_f32_e32 v92, v92, v92
	v_max_f32_e32 v92, 0, v92
	v_mul_f32_e32 v92, v92, v92
	v_max_f32_e32 v93, v93, v93
	v_max_f32_e32 v93, 0, v93
	v_mul_f32_e32 v93, v93, v93
	v_max_f32_e32 v94, v94, v94
	v_max_f32_e32 v94, 0, v94
	v_mul_f32_e32 v94, v94, v94
	v_max_f32_e32 v95, v95, v95
	v_max_f32_e32 v95, 0, v95
	v_mul_f32_e32 v95, v95, v95
	v_max_f32_e32 v88, v88, v88
	v_max_f32_e32 v88, 0, v88
	v_mul_f32_e32 v88, v88, v88
	v_max_f32_e32 v89, v89, v89
	v_max_f32_e32 v89, 0, v89
	v_mul_f32_e32 v89, v89, v89
	v_max_f32_e32 v90, v90, v90
	v_max_f32_e32 v90, 0, v90
	v_mul_f32_e32 v90, v90, v90
	v_max_f32_e32 v91, v91, v91
	v_max_f32_e32 v91, 0, v91
	v_mul_f32_e32 v91, v91, v91
	v_cvt_pk_bf16_f32 v230, v92, v93
	v_cvt_pk_bf16_f32 v231, v94, v95
	v_cvt_pk_bf16_f32 v232, v88, v89
	v_cvt_pk_bf16_f32 v233, v90, v91
	v_add_co_u32_e32 v246, vcc, 0x40000, v244
	v_addc_co_u32_e32 v247, vcc, 0, v245, vcc
	v_permlane16_swap_b32 v230, v232
	v_permlane16_swap_b32 v231, v233
	global_store_dwordx4 v[246:247], v[230:233], off
	v_max_f32_e32 v84, v84, v84
	v_max_f32_e32 v84, 0, v84
	v_mul_f32_e32 v84, v84, v84
	v_max_f32_e32 v85, v85, v85
	v_max_f32_e32 v85, 0, v85
	v_mul_f32_e32 v85, v85, v85
	v_max_f32_e32 v86, v86, v86
	v_max_f32_e32 v86, 0, v86
	v_mul_f32_e32 v86, v86, v86
	v_max_f32_e32 v87, v87, v87
	v_max_f32_e32 v87, 0, v87
	v_mul_f32_e32 v87, v87, v87
	v_max_f32_e32 v80, v80, v80
	v_max_f32_e32 v80, 0, v80
	v_mul_f32_e32 v80, v80, v80
	v_max_f32_e32 v81, v81, v81
	v_max_f32_e32 v81, 0, v81
	v_mul_f32_e32 v81, v81, v81
	v_max_f32_e32 v82, v82, v82
	v_max_f32_e32 v82, 0, v82
	v_mul_f32_e32 v82, v82, v82
	v_max_f32_e32 v83, v83, v83
	v_max_f32_e32 v83, 0, v83
	v_mul_f32_e32 v83, v83, v83
	v_cvt_pk_bf16_f32 v234, v84, v85
	v_cvt_pk_bf16_f32 v235, v86, v87
	v_cvt_pk_bf16_f32 v236, v80, v81
	v_cvt_pk_bf16_f32 v237, v82, v83
	v_add_co_u32_e32 v246, vcc, 0x40100, v244
	v_addc_co_u32_e32 v247, vcc, 0, v245, vcc
	v_permlane16_swap_b32 v234, v236
	v_permlane16_swap_b32 v235, v237
	global_store_dwordx4 v[246:247], v[234:237], off
	v_max_f32_e32 v76, v76, v76
	v_max_f32_e32 v76, 0, v76
	v_mul_f32_e32 v76, v76, v76
	v_max_f32_e32 v77, v77, v77
	v_max_f32_e32 v77, 0, v77
	v_mul_f32_e32 v77, v77, v77
	v_max_f32_e32 v78, v78, v78
	v_max_f32_e32 v78, 0, v78
	v_mul_f32_e32 v78, v78, v78
	v_max_f32_e32 v79, v79, v79
	v_max_f32_e32 v79, 0, v79
	v_mul_f32_e32 v79, v79, v79
	v_max_f32_e32 v72, v72, v72
	v_max_f32_e32 v72, 0, v72
	v_mul_f32_e32 v72, v72, v72
	v_max_f32_e32 v73, v73, v73
	v_max_f32_e32 v73, 0, v73
	v_mul_f32_e32 v73, v73, v73
	v_max_f32_e32 v74, v74, v74
	v_max_f32_e32 v74, 0, v74
	v_mul_f32_e32 v74, v74, v74
	v_max_f32_e32 v75, v75, v75
	v_max_f32_e32 v75, 0, v75
	v_mul_f32_e32 v75, v75, v75
	v_cvt_pk_bf16_f32 v230, v76, v77
	v_cvt_pk_bf16_f32 v231, v78, v79
	v_cvt_pk_bf16_f32 v232, v72, v73
	v_cvt_pk_bf16_f32 v233, v74, v75
	v_add_co_u32_e32 v246, vcc, 0x60000, v244
	v_addc_co_u32_e32 v247, vcc, 0, v245, vcc
	v_permlane16_swap_b32 v230, v232
	v_permlane16_swap_b32 v231, v233
	global_store_dwordx4 v[246:247], v[230:233], off
	v_max_f32_e32 v68, v68, v68
	v_max_f32_e32 v68, 0, v68
	v_mul_f32_e32 v68, v68, v68
	v_max_f32_e32 v69, v69, v69
	v_max_f32_e32 v69, 0, v69
	v_mul_f32_e32 v69, v69, v69
	v_max_f32_e32 v70, v70, v70
	v_max_f32_e32 v70, 0, v70
	v_mul_f32_e32 v70, v70, v70
	v_max_f32_e32 v71, v71, v71
	v_max_f32_e32 v71, 0, v71
	v_mul_f32_e32 v71, v71, v71
	v_max_f32_e32 v64, v64, v64
	v_max_f32_e32 v64, 0, v64
	v_mul_f32_e32 v64, v64, v64
	v_max_f32_e32 v65, v65, v65
	v_max_f32_e32 v65, 0, v65
	v_mul_f32_e32 v65, v65, v65
	v_max_f32_e32 v66, v66, v66
	v_max_f32_e32 v66, 0, v66
	v_mul_f32_e32 v66, v66, v66
	v_max_f32_e32 v67, v67, v67
	v_max_f32_e32 v67, 0, v67
	v_mul_f32_e32 v67, v67, v67
	v_cvt_pk_bf16_f32 v234, v68, v69
	v_cvt_pk_bf16_f32 v235, v70, v71
	v_cvt_pk_bf16_f32 v236, v64, v65
	v_cvt_pk_bf16_f32 v237, v66, v67
	v_add_co_u32_e32 v246, vcc, 0x60100, v244
	v_addc_co_u32_e32 v247, vcc, 0, v245, vcc
	v_permlane16_swap_b32 v234, v236
	v_permlane16_swap_b32 v235, v237
	global_store_dwordx4 v[246:247], v[234:237], off
	v_max_f32_e32 v60, v60, v60
	v_max_f32_e32 v60, 0, v60
	v_mul_f32_e32 v60, v60, v60
	v_max_f32_e32 v61, v61, v61
	v_max_f32_e32 v61, 0, v61
	v_mul_f32_e32 v61, v61, v61
	v_max_f32_e32 v62, v62, v62
	v_max_f32_e32 v62, 0, v62
	v_mul_f32_e32 v62, v62, v62
	v_max_f32_e32 v63, v63, v63
	v_max_f32_e32 v63, 0, v63
	v_mul_f32_e32 v63, v63, v63
	v_max_f32_e32 v56, v56, v56
	v_max_f32_e32 v56, 0, v56
	v_mul_f32_e32 v56, v56, v56
	v_max_f32_e32 v57, v57, v57
	v_max_f32_e32 v57, 0, v57
	v_mul_f32_e32 v57, v57, v57
	v_max_f32_e32 v58, v58, v58
	v_max_f32_e32 v58, 0, v58
	v_mul_f32_e32 v58, v58, v58
	v_max_f32_e32 v59, v59, v59
	v_max_f32_e32 v59, 0, v59
	v_mul_f32_e32 v59, v59, v59
	v_cvt_pk_bf16_f32 v230, v60, v61
	v_cvt_pk_bf16_f32 v231, v62, v63
	v_cvt_pk_bf16_f32 v232, v56, v57
	v_cvt_pk_bf16_f32 v233, v58, v59
	v_add_co_u32_e32 v246, vcc, 0x100000, v244
	v_addc_co_u32_e32 v247, vcc, 0, v245, vcc
	v_permlane16_swap_b32 v230, v232
	v_permlane16_swap_b32 v231, v233
	global_store_dwordx4 v[246:247], v[230:233], off
	v_max_f32_e32 v52, v52, v52
	v_max_f32_e32 v52, 0, v52
	v_mul_f32_e32 v52, v52, v52
	v_max_f32_e32 v53, v53, v53
	v_max_f32_e32 v53, 0, v53
	v_mul_f32_e32 v53, v53, v53
	v_max_f32_e32 v54, v54, v54
	v_max_f32_e32 v54, 0, v54
	v_mul_f32_e32 v54, v54, v54
	v_max_f32_e32 v55, v55, v55
	v_max_f32_e32 v55, 0, v55
	v_mul_f32_e32 v55, v55, v55
	v_max_f32_e32 v48, v48, v48
	v_max_f32_e32 v48, 0, v48
	v_mul_f32_e32 v48, v48, v48
	v_max_f32_e32 v49, v49, v49
	v_max_f32_e32 v49, 0, v49
	v_mul_f32_e32 v49, v49, v49
	v_max_f32_e32 v50, v50, v50
	v_max_f32_e32 v50, 0, v50
	v_mul_f32_e32 v50, v50, v50
	v_max_f32_e32 v51, v51, v51
	v_max_f32_e32 v51, 0, v51
	v_mul_f32_e32 v51, v51, v51
	v_cvt_pk_bf16_f32 v234, v52, v53
	v_cvt_pk_bf16_f32 v235, v54, v55
	v_cvt_pk_bf16_f32 v236, v48, v49
	v_cvt_pk_bf16_f32 v237, v50, v51
	v_add_co_u32_e32 v246, vcc, 0x100100, v244
	v_addc_co_u32_e32 v247, vcc, 0, v245, vcc
	v_permlane16_swap_b32 v234, v236
	v_permlane16_swap_b32 v235, v237
	global_store_dwordx4 v[246:247], v[234:237], off
	v_max_f32_e32 v44, v44, v44
	v_max_f32_e32 v44, 0, v44
	v_mul_f32_e32 v44, v44, v44
	v_max_f32_e32 v45, v45, v45
	v_max_f32_e32 v45, 0, v45
	v_mul_f32_e32 v45, v45, v45
	v_max_f32_e32 v46, v46, v46
	v_max_f32_e32 v46, 0, v46
	v_mul_f32_e32 v46, v46, v46
	v_max_f32_e32 v47, v47, v47
	v_max_f32_e32 v47, 0, v47
	v_mul_f32_e32 v47, v47, v47
	v_max_f32_e32 v40, v40, v40
	v_max_f32_e32 v40, 0, v40
	v_mul_f32_e32 v40, v40, v40
	v_max_f32_e32 v41, v41, v41
	v_max_f32_e32 v41, 0, v41
	v_mul_f32_e32 v41, v41, v41
	v_max_f32_e32 v42, v42, v42
	v_max_f32_e32 v42, 0, v42
	v_mul_f32_e32 v42, v42, v42
	v_max_f32_e32 v43, v43, v43
	v_max_f32_e32 v43, 0, v43
	v_mul_f32_e32 v43, v43, v43
	v_cvt_pk_bf16_f32 v230, v44, v45
	v_cvt_pk_bf16_f32 v231, v46, v47
	v_cvt_pk_bf16_f32 v232, v40, v41
	v_cvt_pk_bf16_f32 v233, v42, v43
	v_add_co_u32_e32 v246, vcc, 0x120000, v244
	v_addc_co_u32_e32 v247, vcc, 0, v245, vcc
	v_permlane16_swap_b32 v230, v232
	v_permlane16_swap_b32 v231, v233
	global_store_dwordx4 v[246:247], v[230:233], off
	v_max_f32_e32 v36, v36, v36
	v_max_f32_e32 v36, 0, v36
	v_mul_f32_e32 v36, v36, v36
	v_max_f32_e32 v37, v37, v37
	v_max_f32_e32 v37, 0, v37
	v_mul_f32_e32 v37, v37, v37
	v_max_f32_e32 v38, v38, v38
	v_max_f32_e32 v38, 0, v38
	v_mul_f32_e32 v38, v38, v38
	v_max_f32_e32 v39, v39, v39
	v_max_f32_e32 v39, 0, v39
	v_mul_f32_e32 v39, v39, v39
	v_max_f32_e32 v32, v32, v32
	v_max_f32_e32 v32, 0, v32
	v_mul_f32_e32 v32, v32, v32
	v_max_f32_e32 v33, v33, v33
	v_max_f32_e32 v33, 0, v33
	v_mul_f32_e32 v33, v33, v33
	v_max_f32_e32 v34, v34, v34
	v_max_f32_e32 v34, 0, v34
	v_mul_f32_e32 v34, v34, v34
	v_max_f32_e32 v35, v35, v35
	v_max_f32_e32 v35, 0, v35
	v_mul_f32_e32 v35, v35, v35
	v_cvt_pk_bf16_f32 v234, v36, v37
	v_cvt_pk_bf16_f32 v235, v38, v39
	v_cvt_pk_bf16_f32 v236, v32, v33
	v_cvt_pk_bf16_f32 v237, v34, v35
	v_add_co_u32_e32 v246, vcc, 0x120100, v244
	v_addc_co_u32_e32 v247, vcc, 0, v245, vcc
	v_permlane16_swap_b32 v234, v236
	v_permlane16_swap_b32 v235, v237
	global_store_dwordx4 v[246:247], v[234:237], off
	v_max_f32_e32 v28, v28, v28
	v_max_f32_e32 v28, 0, v28
	v_mul_f32_e32 v28, v28, v28
	v_max_f32_e32 v29, v29, v29
	v_max_f32_e32 v29, 0, v29
	v_mul_f32_e32 v29, v29, v29
	v_max_f32_e32 v30, v30, v30
	v_max_f32_e32 v30, 0, v30
	v_mul_f32_e32 v30, v30, v30
	v_max_f32_e32 v31, v31, v31
	v_max_f32_e32 v31, 0, v31
	v_mul_f32_e32 v31, v31, v31
	v_max_f32_e32 v24, v24, v24
	v_max_f32_e32 v24, 0, v24
	v_mul_f32_e32 v24, v24, v24
	v_max_f32_e32 v25, v25, v25
	v_max_f32_e32 v25, 0, v25
	v_mul_f32_e32 v25, v25, v25
	v_max_f32_e32 v26, v26, v26
	v_max_f32_e32 v26, 0, v26
	v_mul_f32_e32 v26, v26, v26
	v_max_f32_e32 v27, v27, v27
	v_max_f32_e32 v27, 0, v27
	v_mul_f32_e32 v27, v27, v27
	v_cvt_pk_bf16_f32 v230, v28, v29
	v_cvt_pk_bf16_f32 v231, v30, v31
	v_cvt_pk_bf16_f32 v232, v24, v25
	v_cvt_pk_bf16_f32 v233, v26, v27
	v_add_co_u32_e32 v246, vcc, 0x140000, v244
	v_addc_co_u32_e32 v247, vcc, 0, v245, vcc
	v_permlane16_swap_b32 v230, v232
	v_permlane16_swap_b32 v231, v233
	global_store_dwordx4 v[246:247], v[230:233], off
	v_max_f32_e32 v20, v20, v20
	v_max_f32_e32 v20, 0, v20
	v_mul_f32_e32 v20, v20, v20
	v_max_f32_e32 v21, v21, v21
	v_max_f32_e32 v21, 0, v21
	v_mul_f32_e32 v21, v21, v21
	v_max_f32_e32 v22, v22, v22
	v_max_f32_e32 v22, 0, v22
	v_mul_f32_e32 v22, v22, v22
	v_max_f32_e32 v23, v23, v23
	v_max_f32_e32 v23, 0, v23
	v_mul_f32_e32 v23, v23, v23
	v_max_f32_e32 v16, v16, v16
	v_max_f32_e32 v16, 0, v16
	v_mul_f32_e32 v16, v16, v16
	v_max_f32_e32 v17, v17, v17
	v_max_f32_e32 v17, 0, v17
	v_mul_f32_e32 v17, v17, v17
	v_max_f32_e32 v18, v18, v18
	v_max_f32_e32 v18, 0, v18
	v_mul_f32_e32 v18, v18, v18
	v_max_f32_e32 v19, v19, v19
	v_max_f32_e32 v19, 0, v19
	v_mul_f32_e32 v19, v19, v19
	v_cvt_pk_bf16_f32 v234, v20, v21
	v_cvt_pk_bf16_f32 v235, v22, v23
	v_cvt_pk_bf16_f32 v236, v16, v17
	v_cvt_pk_bf16_f32 v237, v18, v19
	v_add_co_u32_e32 v246, vcc, 0x140100, v244
	v_addc_co_u32_e32 v247, vcc, 0, v245, vcc
	v_permlane16_swap_b32 v234, v236
	v_permlane16_swap_b32 v235, v237
	global_store_dwordx4 v[246:247], v[234:237], off
	v_max_f32_e32 v12, v12, v12
	v_max_f32_e32 v12, 0, v12
	v_mul_f32_e32 v12, v12, v12
	v_max_f32_e32 v13, v13, v13
	v_max_f32_e32 v13, 0, v13
	v_mul_f32_e32 v13, v13, v13
	v_max_f32_e32 v14, v14, v14
	v_max_f32_e32 v14, 0, v14
	v_mul_f32_e32 v14, v14, v14
	v_max_f32_e32 v15, v15, v15
	v_max_f32_e32 v15, 0, v15
	v_mul_f32_e32 v15, v15, v15
	v_max_f32_e32 v8, v8, v8
	v_max_f32_e32 v8, 0, v8
	v_mul_f32_e32 v8, v8, v8
	v_max_f32_e32 v9, v9, v9
	v_max_f32_e32 v9, 0, v9
	v_mul_f32_e32 v9, v9, v9
	v_max_f32_e32 v10, v10, v10
	v_max_f32_e32 v10, 0, v10
	v_mul_f32_e32 v10, v10, v10
	v_max_f32_e32 v11, v11, v11
	v_max_f32_e32 v11, 0, v11
	v_mul_f32_e32 v11, v11, v11
	v_cvt_pk_bf16_f32 v230, v12, v13
	v_cvt_pk_bf16_f32 v231, v14, v15
	v_cvt_pk_bf16_f32 v232, v8, v9
	v_cvt_pk_bf16_f32 v233, v10, v11
	v_add_co_u32_e32 v246, vcc, 0x160000, v244
	v_addc_co_u32_e32 v247, vcc, 0, v245, vcc
	v_permlane16_swap_b32 v230, v232
	v_permlane16_swap_b32 v231, v233
	global_store_dwordx4 v[246:247], v[230:233], off
	v_max_f32_e32 v4, v4, v4
	v_max_f32_e32 v4, 0, v4
	v_mul_f32_e32 v4, v4, v4
	v_max_f32_e32 v5, v5, v5
	v_max_f32_e32 v5, 0, v5
	v_mul_f32_e32 v5, v5, v5
	v_max_f32_e32 v6, v6, v6
	v_max_f32_e32 v6, 0, v6
	v_mul_f32_e32 v6, v6, v6
	v_max_f32_e32 v7, v7, v7
	v_max_f32_e32 v7, 0, v7
	v_mul_f32_e32 v7, v7, v7
	v_max_f32_e32 v0, v0, v0
	v_max_f32_e32 v0, 0, v0
	v_mul_f32_e32 v0, v0, v0
	v_max_f32_e32 v1, v1, v1
	v_max_f32_e32 v1, 0, v1
	v_mul_f32_e32 v1, v1, v1
	v_max_f32_e32 v2, v2, v2
	v_max_f32_e32 v2, 0, v2
	v_mul_f32_e32 v2, v2, v2
	v_max_f32_e32 v3, v3, v3
	v_max_f32_e32 v3, 0, v3
	v_mul_f32_e32 v3, v3, v3
	v_cvt_pk_bf16_f32 v234, v4, v5
	v_cvt_pk_bf16_f32 v235, v6, v7
	v_cvt_pk_bf16_f32 v236, v0, v1
	v_cvt_pk_bf16_f32 v237, v2, v3
	v_add_co_u32_e32 v246, vcc, 0x160100, v244
	v_addc_co_u32_e32 v247, vcc, 0, v245, vcc
	v_permlane16_swap_b32 v234, v236
	v_permlane16_swap_b32 v235, v237
	global_store_dwordx4 v[246:247], v[234:237], off
	s_branch .LBB0_1065
